# grid barrier: the XCD leader no longer waits for its release atomics (XGEN / TOPGEN adds) to complete before leaving the barrier (its invalidate already completed early)
# speedup vs baseline: 1.0027x; 1.0027x over previous
.LBB0_174:
	s_or_b64 exec, exec, s[8:9]
.LBB0_175:
	s_or_b64 exec, exec, s[0:1]
	s_add_u32 s80, s40, 0x7000000
	s_addc_u32 s81, s41, 0
	s_add_u32 s22, s40, 0xb000000
	s_addc_u32 s23, s41, 0
	s_cmpk_lt_i32 s2, 0xb00
	s_waitcnt vmcnt(6) lgkmcnt(0)
	v_mov_b32_e32 v0, v180
	s_waitcnt vmcnt(4)
	v_mov_b32_e32 v9, v182
	s_cselect_b64 s[0:1], -1, 0
	s_barrier
	v_writelane_b32 v230, s0, 1
	s_cmpk_gt_i32 s2, 0xaff
	v_readfirstlane_b32 s5, v9
	v_writelane_b32 v230, s1, 2
	s_cbranch_scc1 .LBB0_191
	v_lshlrev_b32_e32 v0, 4, v9
	v_add_u32_e32 v1, 0x2000, v0
	v_ashrrev_i32_e32 v2, 31, v1
	v_lshrrev_b32_e32 v2, 22, v2
	v_add_u32_e32 v2, v1, v2
	v_ashrrev_i32_e32 v8, 10, v2
	v_mul_i32_i24_e32 v3, 0x400, v8
	v_sub_u32_e32 v1, v1, v3
	v_lshrrev_b32_e32 v3, 4, v1
	v_bitop3_b32 v1, v3, v1, 32 bitop3:0x6c
	v_ashrrev_i32_e32 v3, 31, v1
	v_lshrrev_b32_e32 v3, 26, v3
	s_add_u32 s52, s40, 0x100000
	v_add_u32_e32 v3, v1, v3
	s_addc_u32 s53, s41, 0
	v_ashrrev_i32_e32 v10, 6, v3
	v_and_b32_e32 v3, 0xc0, v3
	s_lshr_b32 s0, s3, 29
	v_sub_u32_e32 v1, v1, v3
	v_mov_b32_e32 v3, 1
	s_add_i32 s0, s2, s0
	s_ashr_i32 s6, s5, 6
	v_lshlrev_b32_e32 v2, 5, v8
	v_ashrrev_i16_sdwa v1, v3, sext(v1) dst_sel:DWORD dst_unused:UNUSED_PAD src0_sel:DWORD src1_sel:BYTE_0
	s_ashr_i32 s1, s0, 3
	s_and_b32 s0, s0, -8
	s_ashr_i32 s8, s5, 8
	s_lshl_b32 s54, s6, 10
	v_and_b32_e32 v2, 32, v2
	v_bfe_i32 v11, v1, 0, 16
	s_sub_i32 s0, s2, s0
	v_add_u32_e32 v1, v2, v11
	v_lshlrev_b32_e32 v2, 3, v8
	s_cmp_lt_i32 s0, 0
	s_movk_i32 s55, 0x161
	v_and_b32_e32 v2, 0x1ffff0, v2
	s_cselect_b32 s4, s55, 0x160
	v_add_lshl_u32 v2, v10, v2, 11
	s_mul_i32 s0, s4, s0
	v_lshl_add_u32 v128, v1, 1, v2
	v_bfe_i32 v2, v9, 27, 1
	s_add_i32 s0, s0, s1
	v_lshrrev_b32_e32 v2, 22, v2
	s_mul_hi_i32 s1, s0, 0x2e8ba2e9
	v_add_u32_e32 v2, v0, v2
	s_lshr_b32 s4, s1, 31
	s_ashr_i32 s1, s1, 5
	v_and_b32_e32 v2, 0xfffffc00, v2
	s_add_i32 s1, s1, s4
	v_sub_u32_e32 v0, v0, v2
	s_lshl_b32 s7, s1, 3
	s_mulk_i32 s1, 0xb0
	v_lshrrev_b32_e32 v2, 4, v0
	s_sub_i32 s0, s0, s1
	v_bitop3_b32 v0, v2, v0, 32 bitop3:0x6c
	s_sext_i32_i16 s1, s0
	v_ashrrev_i32_e32 v2, 31, v0
	s_bfe_u32 s1, s1, 0x3001c
	v_ashrrev_i32_e32 v1, 31, v9
	v_lshrrev_b32_e32 v2, 26, v2
	s_add_i32 s1, s0, s1
	v_lshrrev_b32_e32 v1, 26, v1
	v_add_u32_e32 v2, v0, v2
	s_sext_i32_i16 s4, s1
	s_and_b32 s1, s1, 0xfff8
	v_add_u32_e32 v1, v9, v1
	v_ashrrev_i32_e32 v13, 6, v2
	v_and_b32_e32 v2, 0xc0, v2
	s_sub_i32 s0, s0, s1
	v_ashrrev_i32_e32 v12, 6, v1
	v_sub_u32_e32 v0, v0, v2
	s_sext_i32_i16 s0, s0
	v_lshlrev_b32_e32 v1, 5, v12
	v_ashrrev_i16_sdwa v0, v3, sext(v0) dst_sel:DWORD dst_unused:UNUSED_PAD src0_sel:DWORD src1_sel:BYTE_0
	s_lshr_b32 s4, s4, 3
	s_add_i32 s36, s7, s0
	v_and_b32_e32 v1, 32, v1
	v_bfe_i32 v14, v0, 0, 16
	s_ashr_i32 s37, s36, 31
	s_bfe_i64 s[10:11], s[4:5], 0x100000
	v_add_u32_e32 v0, v1, v14
	v_lshlrev_b32_e32 v1, 3, v12
	s_lshl_b64 s[0:1], s[36:37], 19
	s_lshl_b64 s[10:11], s[10:11], 19
	v_and_b32_e32 v1, 0x1ffff0, v1
	s_add_u32 s46, s52, s10
	v_add_lshl_u32 v1, v13, v1, 11
	s_addc_u32 s47, s53, s11
	s_add_i32 s37, s54, 0
	v_lshl_add_u32 v130, v0, 1, v1
	s_add_i32 m0, s37, 0x10000
	v_mov_b32_e32 v131, 0
	global_load_lds_dwordx4 v130, s[46:47]
	s_add_i32 m0, s37, 0x12000
	s_add_u32 s10, s46, 0x40000
	global_load_lds_dwordx4 v128, s[46:47]
	s_addc_u32 s11, s47, 0
	s_add_i32 m0, s37, 0x14000
	v_mov_b32_e32 v129, v131
	global_load_lds_dwordx4 v130, s[10:11]
	s_add_i32 m0, s37, 0x16000
	s_add_u32 s44, s80, s0
	s_addc_u32 s45, s81, s1
	s_add_i32 s56, s37, 0x2000
	global_load_lds_dwordx4 v128, s[10:11]
	s_mov_b32 m0, s37
	s_add_u32 s0, s44, 0x40000
	global_load_lds_dwordx4 v130, s[44:45]
	s_mov_b32 m0, s56
	s_addc_u32 s1, s45, 0
	s_add_i32 s57, s37, 0x4000
	global_load_lds_dwordx4 v128, s[44:45]
	s_mov_b32 m0, s57
	s_add_i32 s58, s37, 0x6000
	global_load_lds_dwordx4 v130, s[0:1]
	s_mov_b32 m0, s58
	s_cmp_eq_u32 s8, 1
	global_load_lds_dwordx4 v128, s[0:1]
	s_mov_b32 s59, 0
	v_lshl_add_u64 v[6:7], s[46:47], 0, v[130:131]
	v_lshl_add_u64 v[4:5], s[46:47], 0, v[128:129]
	v_lshl_add_u64 v[0:1], s[44:45], 0, v[130:131]
	s_cselect_b64 s[0:1], -1, 0
	s_cmp_lg_u32 s8, 1
	v_lshl_add_u64 v[2:3], s[44:45], 0, v[128:129]
	s_cbranch_scc1 .LBB0_178
	s_barrier

.LBB0_242:
	s_or_b64 exec, exec, s[8:9]
.LBB0_243:
	s_or_b64 exec, exec, s[0:1]
	s_add_u32 s24, s40, 0x17000000
	s_addc_u32 s25, s41, 0
	s_waitcnt lgkmcnt(0)
	v_mov_b32_e32 v0, v180
	v_mov_b32_e32 v8, v182
	s_cmpk_lt_i32 s2, 0x200
	s_barrier
	s_cselect_b64 s[12:13], -1, 0
	s_cmpk_gt_i32 s2, 0x1ff
	v_readfirstlane_b32 s4, v8
	s_cbranch_scc1 .LBB0_271
	s_lshr_b32 s0, s3, 29
	s_add_i32 s5, s2, s0
	s_and_b32 s0, s5, -8
	s_sub_i32 s6, s2, s0
	s_cmp_gt_i32 s6, -1
	s_cbranch_scc0 .LBB0_246
	s_lshl_b32 s8, s6, 6
	s_cbranch_execz .LBB0_247
	s_branch .LBB0_248

.LBB0_322:
	s_or_b64 exec, exec, s[8:9]
.LBB0_323:
	s_or_b64 exec, exec, s[0:1]
	s_cmpk_lt_i32 s33, 0x2000
	s_waitcnt lgkmcnt(0)
	v_mov_b32_e32 v0, v180
	s_movk_i32 s57, 0x2000
	s_cselect_b64 s[30:31], -1, 0
	s_cmpk_gt_i32 s33, 0x1fff
	v_mbcnt_lo_u32_b32 v183, -1, 0
	s_barrier
	s_cbranch_scc1 .LBB0_326
	v_mbcnt_hi_u32_b32 v2, -1, v183
	v_and_b32_e32 v3, 64, v2
	v_add_u32_e32 v3, 64, v3
	v_xor_b32_e32 v4, 1, v2
	v_cmp_lt_i32_e32 vcc, v4, v3
	s_lshl_b32 s36, s33, 2
	s_ashr_i32 s37, s36, 31
	v_cndmask_b32_e32 v4, v2, v4, vcc
	v_lshlrev_b32_e32 v86, 2, v4
	v_xor_b32_e32 v4, 2, v2
	v_cmp_lt_i32_e32 vcc, v4, v3
	s_lshl_b32 s44, s42, 5
	s_lshl_b64 s[0:1], s[36:37], 9
	v_cndmask_b32_e32 v4, v2, v4, vcc
	v_lshlrev_b32_e32 v87, 2, v4
	v_xor_b32_e32 v4, 4, v2
	v_cmp_lt_i32_e32 vcc, v4, v3
	s_add_u32 s46, s40, s0
	s_addc_u32 s47, s41, s1
	v_cndmask_b32_e32 v4, v2, v4, vcc
	v_lshlrev_b32_e32 v88, 2, v4
	v_xor_b32_e32 v4, 8, v2
	v_cmp_lt_i32_e32 vcc, v4, v3
	s_ashr_i32 s45, s44, 31
	s_lshl_b64 s[48:49], s[44:45], 9
	v_cndmask_b32_e32 v4, v2, v4, vcc
	v_lshlrev_b32_e32 v89, 2, v4
	v_xor_b32_e32 v4, 16, v2
	v_cmp_lt_i32_e32 vcc, v4, v3
	s_lshl_b64 s[0:1], s[36:37], 11
	s_add_u32 s52, s40, s0
	v_cndmask_b32_e32 v4, v2, v4, vcc
	v_lshlrev_b32_e32 v90, 2, v4
	v_xor_b32_e32 v4, 32, v2
	v_cmp_lt_i32_e32 vcc, v4, v3
	s_addc_u32 s53, s41, s1
	s_lshl_b64 s[54:55], s[44:45], 11
	s_lshl_b64 s[0:1], s[36:37], 12
	v_ashrrev_i32_e32 v1, 31, v0
	v_cndmask_b32_e32 v2, v2, v4, vcc
	s_add_u32 s0, s16, s0
	v_lshlrev_b32_e32 v91, 2, v2
	v_lshlrev_b64 v[2:3], 4, v[0:1]
	s_addc_u32 s1, s17, s1
	v_lshl_add_u64 v[24:25], s[26:27], 0, v[2:3]
	v_lshl_add_u64 v[26:27], s[28:29], 0, v[2:3]
	v_lshlrev_b64 v[28:29], 3, v[0:1]
	v_lshl_add_u64 v[30:31], s[0:1], 0, v[2:3]
	s_lshl_b64 s[16:17], s[44:45], 12
	s_mov_b32 s56, 0x3fb504f3
	v_mov_b32_e32 v92, 0x3727c5ac
	s_mov_b32 s37, 0xf800000
	v_mov_b32_e32 v93, 0x260
	s_movk_i32 s45, 0x7fff
	s_mov_b32 s58, 0x7000000
	s_mov_b32 s59, 0x7001000
	s_mov_b32 s60, 0x1b400000

.LBB0_377:
	s_or_b64 exec, exec, s[8:9]
.LBB0_378:
	s_or_b64 exec, exec, s[0:1]
	s_waitcnt lgkmcnt(0)
	v_mov_b32_e32 v0, v180
	v_mov_b32_e32 v9, v182
	s_barrier
	s_cmpk_gt_i32 s2, 0x5ff
	v_readfirstlane_b32 s5, v9
	s_cbranch_scc1 .LBB0_394
	v_lshlrev_b32_e32 v0, 4, v9
	v_add_u32_e32 v1, 0x2000, v0
	v_ashrrev_i32_e32 v2, 31, v1
	v_lshrrev_b32_e32 v2, 22, v2
	v_add_u32_e32 v2, v1, v2
	v_ashrrev_i32_e32 v8, 10, v2
	v_mul_i32_i24_e32 v2, 0x400, v8
	v_sub_u32_e32 v1, v1, v2
	v_lshrrev_b32_e32 v2, 4, v1
	v_bitop3_b32 v1, v2, v1, 32 bitop3:0x6c
	v_ashrrev_i32_e32 v2, 31, v1
	v_lshrrev_b32_e32 v2, 26, v2
	v_add_u32_e32 v2, v1, v2
	v_lshlrev_b32_e32 v3, 3, v8
	v_ashrrev_i32_e32 v10, 6, v2
	v_and_b32_e32 v3, -16, v3
	v_add_u32_e32 v3, v10, v3
	v_and_b32_e32 v4, 3, v10
	s_mov_b32 s0, 0x1fffe0
	v_lshrrev_b32_e32 v5, 2, v3
	v_lshlrev_b32_e32 v6, 1, v3
	v_and_b32_e32 v2, 0xc0, v2
	v_and_or_b32 v4, v3, s0, v4
	v_and_b32_e32 v5, 4, v5
	v_and_b32_e32 v6, 24, v6
	v_sub_u32_e32 v1, v1, v2
	v_mov_b32_e32 v2, 1
	v_or3_b32 v4, v4, v5, v6
	v_lshlrev_b32_e32 v5, 5, v8
	v_ashrrev_i16_sdwa v1, v2, sext(v1) dst_sel:DWORD dst_unused:UNUSED_PAD src0_sel:DWORD src1_sel:BYTE_0
	v_and_b32_e32 v5, 32, v5
	v_bfe_i32 v11, v1, 0, 16
	v_add_lshl_u32 v1, v5, v11, 1
	v_lshl_add_u32 v128, v4, 11, v1
	v_lshl_add_u32 v130, v3, 11, v1
	v_bfe_i32 v1, v9, 27, 1
	v_lshrrev_b32_e32 v1, 22, v1
	v_add_u32_e32 v1, v0, v1
	v_and_b32_e32 v1, 0xfffffc00, v1
	v_sub_u32_e32 v0, v0, v1
	v_lshrrev_b32_e32 v1, 4, v0
	v_ashrrev_i32_e32 v3, 31, v9
	v_bitop3_b32 v0, v1, v0, 32 bitop3:0x6c
	v_lshrrev_b32_e32 v3, 26, v3
	v_ashrrev_i32_e32 v1, 31, v0
	v_add_u32_e32 v3, v9, v3
	v_lshrrev_b32_e32 v1, 26, v1
	v_ashrrev_i32_e32 v13, 6, v3
	v_add_u32_e32 v1, v0, v1
	v_lshlrev_b32_e32 v3, 3, v13
	v_ashrrev_i32_e32 v12, 6, v1
	v_and_b32_e32 v3, -16, v3
	s_add_u32 s64, s40, 0x4300000
	v_add_u32_e32 v3, v12, v3
	v_and_b32_e32 v4, 3, v12
	s_addc_u32 s65, s41, 0
	v_and_or_b32 v4, v3, s0, v4
	s_lshr_b32 s0, s3, 29
	s_add_i32 s0, s2, s0
	s_ashr_i32 s6, s5, 6
	s_ashr_i32 s1, s0, 3
	s_and_b32 s0, s0, -8
	s_ashr_i32 s8, s5, 8
	s_lshl_b32 s66, s6, 10
	s_sub_i32 s0, s2, s0
	s_cmp_lt_i32 s0, 0
	s_movk_i32 s67, 0xc1
	s_cselect_b32 s4, s67, 0xc0
	s_mul_i32 s0, s4, s0
	s_add_i32 s0, s0, s1
	s_mul_hi_i32 s1, s0, 0x2aaaaaab
	s_lshr_b32 s4, s1, 31
	s_ashr_i32 s1, s1, 4
	s_add_i32 s1, s1, s4
	s_lshl_b32 s7, s1, 3
	s_mulk_i32 s1, 0x60
	s_sub_i32 s0, s0, s1
	s_bfe_i32 s1, s0, 0x80000
	s_bfe_u32 s1, s1, 0x3000c
	s_add_i32 s1, s0, s1
	s_bfe_i32 s4, s1, 0x80000
	s_and_b32 s1, s1, 0xf8
	s_sub_i32 s0, s0, s1
	s_sext_i32_i16 s4, s4
	s_sext_i32_i8 s0, s0
	v_lshrrev_b32_e32 v5, 2, v3
	v_lshlrev_b32_e32 v6, 1, v3
	v_and_b32_e32 v1, 0xc0, v1
	s_lshr_b32 s4, s4, 3
	s_add_i32 s56, s7, s0
	v_and_b32_e32 v5, 4, v5
	v_and_b32_e32 v6, 24, v6
	v_sub_u32_e32 v0, v0, v1
	s_ashr_i32 s57, s56, 31
	s_bfe_i64 s[10:11], s[4:5], 0x100000
	v_or3_b32 v4, v4, v5, v6
	v_lshlrev_b32_e32 v5, 5, v13
	v_ashrrev_i16_sdwa v0, v2, sext(v0) dst_sel:DWORD dst_unused:UNUSED_PAD src0_sel:DWORD src1_sel:BYTE_0
	s_lshl_b64 s[0:1], s[56:57], 19
	s_lshl_b64 s[10:11], s[10:11], 19
	v_and_b32_e32 v5, 32, v5
	v_bfe_i32 v14, v0, 0, 16
	s_add_u32 s60, s64, s10
	v_add_lshl_u32 v0, v5, v14, 1
	s_addc_u32 s61, s65, s11
	s_add_i32 s68, s66, 0
	v_lshl_add_u32 v132, v4, 11, v0
	s_add_i32 m0, s68, 0x10000
	v_lshl_add_u32 v134, v3, 11, v0
	global_load_lds_dwordx4 v132, s[60:61]
	s_add_i32 m0, s68, 0x12000
	s_add_u32 s10, s60, 0x40000
	global_load_lds_dwordx4 v128, s[60:61]
	s_addc_u32 s11, s61, 0
	s_add_i32 m0, s68, 0x14000
	v_mov_b32_e32 v133, 0
	global_load_lds_dwordx4 v132, s[10:11]
	s_add_i32 m0, s68, 0x16000
	s_add_u32 s58, s80, s0
	s_addc_u32 s59, s81, s1
	s_add_i32 s69, s68, 0x2000
	global_load_lds_dwordx4 v128, s[10:11]
	s_mov_b32 m0, s68
	s_add_u32 s0, s58, 0x40000
	global_load_lds_dwordx4 v134, s[58:59]
	s_mov_b32 m0, s69
	s_addc_u32 s1, s59, 0
	s_add_i32 s70, s68, 0x4000
	global_load_lds_dwordx4 v130, s[58:59]
	s_mov_b32 m0, s70
	s_add_i32 s71, s68, 0x6000
	global_load_lds_dwordx4 v134, s[0:1]
	s_mov_b32 m0, s71
	v_mov_b32_e32 v129, v133
	global_load_lds_dwordx4 v130, s[0:1]
	v_mov_b32_e32 v135, v133
	v_mov_b32_e32 v131, v133
	s_cmp_eq_u32 s8, 1
	s_mov_b32 s72, 0
	v_lshl_add_u64 v[6:7], s[60:61], 0, v[132:133]
	v_lshl_add_u64 v[4:5], s[60:61], 0, v[128:129]
	v_lshl_add_u64 v[0:1], s[58:59], 0, v[134:135]
	s_cselect_b64 s[0:1], -1, 0
	s_cmp_lg_u32 s8, 1
	v_lshl_add_u64 v[2:3], s[58:59], 0, v[130:131]
	s_cbranch_scc1 .LBB0_381
	s_barrier

.LBB0_445:
	s_or_b64 exec, exec, s[8:9]
.LBB0_446:
	s_or_b64 exec, exec, s[0:1]
	s_add_u32 s8, s40, 0xf000000
	s_addc_u32 s9, s41, 0
	s_add_u32 s10, s40, 0x13000000
	s_waitcnt lgkmcnt(0)
	v_mov_b32_e32 v0, v180
	s_addc_u32 s11, s41, 0
	v_mov_b32_e32 v4, v182
	s_barrier
	s_cmpk_gt_i32 s2, 0xfff
	v_readfirstlane_b32 s5, v4
	s_cbranch_scc1 .LBB0_463
	s_and_b32 s0, s2, 0x7ff
	s_cmpk_lt_u32 s2, 0x800
	s_cselect_b32 s60, 16, 4
	s_cselect_b32 s1, 0, 3
	s_cselect_b32 s6, 0, 2
	s_cselect_b32 s4, 4, 2
	s_and_b32 s7, s1, s2
	s_lshr_b32 s0, s0, s6
	s_add_i32 s1, s60, -1
	s_and_b32 s61, s0, s1
	s_lshr_b32 s0, s0, s4
	s_and_b32 s63, s0, 15
	s_lshr_b32 s16, s0, 4
	s_lshl_b32 s0, s16, 18
	s_lshl_b32 s1, s63, 21
	s_add_i32 s1, s1, s0
	s_lshl_b32 s95, s7, 8
	s_lshl_b32 s6, s1, 1
	s_add_u32 s36, s8, s6
	s_addc_u32 s37, s9, 0
	s_add_u32 s44, s10, s6
	v_lshrrev_b32_e32 v160, 3, v4
	v_lshlrev_b32_e32 v1, 4, v4
	s_addc_u32 s45, s11, 0
	v_lshlrev_b32_e32 v0, s4, v160
	v_and_b32_e32 v161, 0x70, v1
	v_lshl_or_b32 v80, v0, 7, v161
	s_cmp_lg_u32 s7, 0
	v_mov_b32_e32 v81, 0
	s_cselect_b64 s[0:1], -1, 0
	s_cmp_eq_u32 s7, 0
	v_lshl_add_u64 v[0:1], s[36:37], 0, v[80:81]
	v_lshl_add_u64 v[2:3], s[44:45], 0, v[80:81]
	s_cbranch_scc1 .LBB0_450
	s_add_i32 s36, s95, 0xffffff80
	s_ashr_i32 s37, s36, 31
	s_lshl_b64 s[36:37], s[36:37], s4
	s_add_u32 s36, s36, s61
	s_addc_u32 s37, s37, 0
	s_lshl_b64 s[36:37], s[36:37], 7
	v_lshl_add_u64 v[6:7], v[0:1], 0, s[36:37]
	v_lshl_add_u64 v[8:9], v[2:3], 0, s[36:37]
	global_load_dwordx4 v[84:87], v[6:7], off nt
	global_load_dwordx4 v[80:83], v[8:9], off nt
	s_andn2_b64 vcc, exec, s[0:1]
	s_mov_b32 s17, 0
	s_cbranch_vccnz .LBB0_451

.LBB0_514:
	s_or_b64 exec, exec, s[16:17]
.LBB0_515:
	s_or_b64 exec, exec, s[0:1]
	s_waitcnt lgkmcnt(0)
	v_mov_b32_e32 v0, v180
	v_mov_b32_e32 v6, v182
	s_barrier
	s_cmpk_gt_i32 s2, 0x7ff
	v_readfirstlane_b32 s16, v6
	s_cbranch_scc1 .LBB0_532
	s_lshl_b32 s0, s2, 8
	s_and_b32 s63, s0, 0xf00
	s_ashr_i32 s0, s2, 8
	s_bfe_u32 s62, s2, 0x40004
	s_ashr_i32 s1, s0, 31
	s_lshl_b64 s[4:5], s[0:1], 18
	s_lshl_b32 s1, s62, 21
	s_add_u32 s4, s4, s1
	s_addc_u32 s5, s5, 0
	s_lshl_b64 s[4:5], s[4:5], 1
	s_add_u32 s18, s8, s4
	s_addc_u32 s19, s9, s5
	s_add_u32 s36, s10, s4
	s_addc_u32 s37, s11, s5
	v_lshlrev_b32_e32 v0, 4, v6
	s_cmp_lg_u32 s63, 0
	v_mov_b32_e32 v1, 0
	s_cselect_b64 s[6:7], -1, 0
	s_cmp_eq_u32 s63, 0
	v_lshl_add_u64 v[2:3], s[18:19], 0, v[0:1]
	v_lshl_add_u64 v[4:5], s[36:37], 0, v[0:1]
	s_cbranch_scc1 .LBB0_519
	s_lshl_b32 s1, s63, 7
	s_add_u32 s18, s1, 0xffffc000
	s_addc_u32 s19, 0, -1
	v_lshl_add_u64 v[8:9], v[2:3], 0, s[18:19]
	v_lshl_add_u64 v[10:11], v[4:5], 0, s[18:19]
	global_load_dwordx4 v[84:87], v[8:9], off nt
	global_load_dwordx4 v[80:83], v[10:11], off nt
	s_andn2_b64 vcc, exec, s[6:7]
	s_mov_b32 s17, 0
	s_cbranch_vccnz .LBB0_520

.LBB0_583:
	s_or_b64 exec, exec, s[8:9]
.LBB0_584:
	s_or_b64 exec, exec, s[0:1]
	s_waitcnt lgkmcnt(0)
	v_mov_b32_e32 v0, v180
	s_barrier
	v_mov_b32_e32 v8, v182
	v_cndmask_b32_e64 v0, 0, 1, s[12:13]
	v_cmp_ne_u32_e64 s[6:7], 1, v0
	s_andn2_b64 vcc, exec, s[12:13]
	v_readfirstlane_b32 s5, v8
	s_cbranch_vccnz .LBB0_608
	s_lshr_b32 s0, s3, 29
	s_add_i32 s8, s2, s0
	s_and_b32 s0, s8, -8
	s_sub_i32 s9, s2, s0
	s_cmp_gt_i32 s9, -1
	s_cbranch_scc0 .LBB0_587
	s_lshl_b32 s4, s9, 6
	s_cbranch_execz .LBB0_588
	s_branch .LBB0_589

.LBB0_659:
	s_or_b64 exec, exec, s[10:11]
.LBB0_660:
	s_or_b64 exec, exec, s[0:1]
	v_cndmask_b32_e64 v1, 0, 1, s[30:31]
	s_waitcnt lgkmcnt(0)
	v_mov_b32_e32 v0, v180
	v_cmp_ne_u32_e64 s[4:5], 1, v1
	s_andn2_b64 vcc, exec, s[30:31]
	s_barrier
	s_cbranch_vccnz .LBB0_663
	v_mbcnt_hi_u32_b32 v2, -1, v183
	v_and_b32_e32 v3, 64, v2
	v_add_u32_e32 v3, 64, v3
	v_xor_b32_e32 v4, 1, v2
	v_cmp_lt_i32_e32 vcc, v4, v3
	v_ashrrev_i32_e32 v1, 31, v0
	s_lshl_b32 s30, s33, 2
	v_cndmask_b32_e32 v4, v2, v4, vcc
	v_lshlrev_b32_e32 v98, 2, v4
	v_xor_b32_e32 v4, 2, v2
	v_cmp_lt_i32_e32 vcc, v4, v3
	s_mov_b64 s[0:1], 0x1000
	s_ashr_i32 s31, s30, 31
	v_cndmask_b32_e32 v4, v2, v4, vcc
	v_lshlrev_b32_e32 v99, 2, v4
	v_xor_b32_e32 v4, 4, v2
	v_cmp_lt_i32_e32 vcc, v4, v3
	s_lshl_b32 s36, s42, 5
	v_lshlrev_b64 v[12:13], 3, v[0:1]
	v_cndmask_b32_e32 v4, v2, v4, vcc
	v_lshlrev_b32_e32 v100, 2, v4
	v_xor_b32_e32 v4, 8, v2
	v_cmp_lt_i32_e32 vcc, v4, v3
	s_mov_b32 s55, 0x17001000
	s_mov_b32 s54, 0x3fb504f3
	v_cndmask_b32_e32 v4, v2, v4, vcc
	v_lshlrev_b32_e32 v101, 2, v4
	v_xor_b32_e32 v4, 16, v2
	v_cmp_lt_i32_e32 vcc, v4, v3
	v_mov_b32_e32 v104, 0x3727c5ac
	s_mov_b32 s56, 0xf800000
	v_cndmask_b32_e32 v4, v2, v4, vcc
	v_lshlrev_b32_e32 v102, 2, v4
	v_xor_b32_e32 v4, 32, v2
	v_cmp_lt_i32_e32 vcc, v4, v3
	v_mov_b32_e32 v105, 0x260
	s_movk_i32 s57, 0x7fff
	v_cndmask_b32_e32 v2, v2, v4, vcc
	v_lshlrev_b32_e32 v103, 2, v2
	v_lshlrev_b64 v[2:3], 4, v[0:1]
	v_lshl_add_u64 v[4:5], s[26:27], 0, v[2:3]
	v_lshl_add_u64 v[2:3], s[28:29], 0, v[2:3]
	v_lshl_add_u64 v[8:9], v[4:5], 0, s[0:1]
	v_lshl_add_u64 v[10:11], v[2:3], 0, s[0:1]
	s_lshl_b64 s[0:1], s[30:31], 9
	s_add_u32 s44, s40, s0
	s_addc_u32 s45, s41, s1
	s_ashr_i32 s37, s36, 31
	s_lshl_b64 s[46:47], s[36:37], 9
	s_lshl_b64 s[0:1], s[30:31], 11
	s_add_u32 s48, s40, s0
	s_addc_u32 s49, s41, s1
	s_lshl_b64 s[52:53], s[36:37], 11
	s_movk_i32 s31, 0xf000
	s_mov_b32 s37, 0x17000000

.LBB0_714:
	s_or_b64 exec, exec, s[12:13]
.LBB0_715:
	s_or_b64 exec, exec, s[0:1]
	s_waitcnt lgkmcnt(0)
	v_mov_b32_e32 v0, v180
	v_readlane_b32 s0, v230, 1
	s_barrier
	v_readlane_b32 s1, v230, 2
	v_mov_b32_e32 v9, v182
	s_andn2_b64 vcc, exec, s[0:1]
	v_cndmask_b32_e64 v0, 0, 1, s[0:1]
	v_cmp_ne_u32_e64 s[8:9], 1, v0
	v_readfirstlane_b32 s11, v9
	s_cbranch_vccnz .LBB0_731
	v_lshlrev_b32_e32 v0, 4, v9
	v_add_u32_e32 v1, 0x2000, v0
	v_ashrrev_i32_e32 v2, 31, v1
	v_lshrrev_b32_e32 v2, 22, v2
	v_add_u32_e32 v2, v1, v2
	v_ashrrev_i32_e32 v8, 10, v2
	v_mul_i32_i24_e32 v3, 0x400, v8
	v_sub_u32_e32 v1, v1, v3
	v_lshrrev_b32_e32 v3, 4, v1
	v_bitop3_b32 v1, v3, v1, 32 bitop3:0x6c
	v_ashrrev_i32_e32 v3, 31, v1
	v_lshrrev_b32_e32 v3, 26, v3
	s_add_u32 s56, s40, 0x1700000
	v_add_u32_e32 v3, v1, v3
	s_addc_u32 s57, s41, 0
	v_ashrrev_i32_e32 v10, 6, v3
	v_and_b32_e32 v3, 0xc0, v3
	s_lshr_b32 s0, s3, 29
	v_sub_u32_e32 v1, v1, v3
	v_mov_b32_e32 v3, 1
	s_add_i32 s0, s2, s0
	s_ashr_i32 s12, s11, 6
	v_lshlrev_b32_e32 v2, 5, v8
	v_ashrrev_i16_sdwa v1, v3, sext(v1) dst_sel:DWORD dst_unused:UNUSED_PAD src0_sel:DWORD src1_sel:BYTE_0
	s_ashr_i32 s1, s0, 3
	s_and_b32 s0, s0, -8
	s_ashr_i32 s16, s11, 8
	s_lshl_b32 s58, s12, 10
	v_and_b32_e32 v2, 32, v2
	v_bfe_i32 v11, v1, 0, 16
	s_sub_i32 s0, s2, s0
	v_add_u32_e32 v1, v2, v11
	v_lshlrev_b32_e32 v2, 3, v8
	s_cmp_lt_i32 s0, 0
	s_movk_i32 s59, 0x161
	v_and_b32_e32 v2, 0x1ffff0, v2
	s_cselect_b32 s10, s59, 0x160
	v_add_lshl_u32 v2, v10, v2, 11
	s_mul_i32 s0, s10, s0
	v_lshl_add_u32 v128, v1, 1, v2
	v_bfe_i32 v2, v9, 27, 1
	s_add_i32 s0, s0, s1
	v_lshrrev_b32_e32 v2, 22, v2
	s_mul_hi_i32 s1, s0, 0x2e8ba2e9
	v_add_u32_e32 v2, v0, v2
	s_lshr_b32 s10, s1, 31
	s_ashr_i32 s1, s1, 5
	v_and_b32_e32 v2, 0xfffffc00, v2
	s_add_i32 s1, s1, s10
	v_sub_u32_e32 v0, v0, v2
	s_lshl_b32 s13, s1, 3
	s_mulk_i32 s1, 0xb0
	v_lshrrev_b32_e32 v2, 4, v0
	s_sub_i32 s0, s0, s1
	v_bitop3_b32 v0, v2, v0, 32 bitop3:0x6c
	s_sext_i32_i16 s1, s0
	v_ashrrev_i32_e32 v2, 31, v0
	s_bfe_u32 s1, s1, 0x3001c
	v_ashrrev_i32_e32 v1, 31, v9
	v_lshrrev_b32_e32 v2, 26, v2
	s_add_i32 s1, s0, s1
	v_lshrrev_b32_e32 v1, 26, v1
	v_add_u32_e32 v2, v0, v2
	s_sext_i32_i16 s10, s1
	s_and_b32 s1, s1, 0xfff8
	v_add_u32_e32 v1, v9, v1
	v_ashrrev_i32_e32 v13, 6, v2
	v_and_b32_e32 v2, 0xc0, v2
	s_sub_i32 s0, s0, s1
	v_ashrrev_i32_e32 v12, 6, v1
	v_sub_u32_e32 v0, v0, v2
	s_sext_i32_i16 s0, s0
	v_lshlrev_b32_e32 v1, 5, v12
	v_ashrrev_i16_sdwa v0, v3, sext(v0) dst_sel:DWORD dst_unused:UNUSED_PAD src0_sel:DWORD src1_sel:BYTE_0
	s_lshr_b32 s10, s10, 3
	s_add_i32 s46, s13, s0
	v_and_b32_e32 v1, 32, v1
	v_bfe_i32 v14, v0, 0, 16
	s_ashr_i32 s47, s46, 31
	s_bfe_i64 s[18:19], s[10:11], 0x100000
	v_add_u32_e32 v0, v1, v14
	v_lshlrev_b32_e32 v1, 3, v12
	s_lshl_b64 s[0:1], s[46:47], 19
	s_lshl_b64 s[18:19], s[18:19], 19
	v_and_b32_e32 v1, 0x1ffff0, v1
	s_add_u32 s52, s56, s18
	v_add_lshl_u32 v1, v13, v1, 11
	s_addc_u32 s53, s57, s19
	s_add_i32 s47, s58, 0
	v_lshl_add_u32 v130, v0, 1, v1
	s_add_i32 m0, s47, 0x10000
	v_mov_b32_e32 v131, 0
	global_load_lds_dwordx4 v130, s[52:53]
	s_add_i32 m0, s47, 0x12000
	s_add_u32 s18, s52, 0x40000
	global_load_lds_dwordx4 v128, s[52:53]
	s_addc_u32 s19, s53, 0
	s_add_i32 m0, s47, 0x14000
	v_mov_b32_e32 v129, v131
	global_load_lds_dwordx4 v130, s[18:19]
	s_add_i32 m0, s47, 0x16000
	s_add_u32 s48, s80, s0
	s_addc_u32 s49, s81, s1
	s_add_i32 s60, s47, 0x2000
	global_load_lds_dwordx4 v128, s[18:19]
	s_mov_b32 m0, s47
	s_add_u32 s0, s48, 0x40000
	global_load_lds_dwordx4 v130, s[48:49]
	s_mov_b32 m0, s60
	s_addc_u32 s1, s49, 0
	s_add_i32 s61, s47, 0x4000
	global_load_lds_dwordx4 v128, s[48:49]
	s_mov_b32 m0, s61
	s_add_i32 s62, s47, 0x6000
	global_load_lds_dwordx4 v130, s[0:1]
	s_mov_b32 m0, s62
	s_cmp_eq_u32 s16, 1
	global_load_lds_dwordx4 v128, s[0:1]
	s_mov_b32 s63, 0
	v_lshl_add_u64 v[6:7], s[52:53], 0, v[130:131]
	v_lshl_add_u64 v[4:5], s[52:53], 0, v[128:129]
	v_lshl_add_u64 v[0:1], s[48:49], 0, v[130:131]
	s_cselect_b64 s[0:1], -1, 0
	s_cmp_lg_u32 s16, 1
	v_lshl_add_u64 v[2:3], s[48:49], 0, v[128:129]
	s_cbranch_scc1 .LBB0_718
	s_barrier

.LBB0_782:
	s_or_b64 exec, exec, s[16:17]
.LBB0_783:
	s_or_b64 exec, exec, s[0:1]
	s_waitcnt lgkmcnt(0)
	v_mov_b32_e32 v0, v180
	v_mov_b32_e32 v8, v182
	s_barrier
	s_and_b64 vcc, exec, s[6:7]
	v_readfirstlane_b32 s10, v8
	s_cbranch_vccnz .LBB0_811
	s_lshr_b32 s0, s3, 29
	s_add_i32 s11, s2, s0
	s_and_b32 s0, s11, -8
	s_sub_i32 s12, s2, s0
	s_cmp_gt_i32 s12, -1
	s_cbranch_scc0 .LBB0_786
	s_lshl_b32 s16, s12, 6
	s_cbranch_execz .LBB0_787
	s_branch .LBB0_788

.LBB0_862:
	s_or_b64 exec, exec, s[16:17]
.LBB0_863:
	s_or_b64 exec, exec, s[0:1]
	s_waitcnt lgkmcnt(0)
	v_mov_b32_e32 v0, v180
	s_and_b64 vcc, exec, s[4:5]
	s_barrier
	s_cbranch_vccnz .LBB0_866
	v_mbcnt_hi_u32_b32 v2, -1, v183
	v_and_b32_e32 v3, 64, v2
	v_add_u32_e32 v3, 64, v3
	v_xor_b32_e32 v4, 1, v2
	v_cmp_lt_i32_e32 vcc, v4, v3
	v_ashrrev_i32_e32 v1, 31, v0
	s_lshl_b32 s30, s33, 2
	v_cndmask_b32_e32 v4, v2, v4, vcc
	v_lshlrev_b32_e32 v84, 2, v4
	v_xor_b32_e32 v4, 2, v2
	v_cmp_lt_i32_e32 vcc, v4, v3
	s_mov_b64 s[0:1], 0x2000
	s_ashr_i32 s31, s30, 31
	v_cndmask_b32_e32 v4, v2, v4, vcc
	v_lshlrev_b32_e32 v85, 2, v4
	v_xor_b32_e32 v4, 4, v2
	v_cmp_lt_i32_e32 vcc, v4, v3
	s_lshl_b32 s36, s42, 5
	v_lshlrev_b64 v[12:13], 3, v[0:1]
	v_cndmask_b32_e32 v4, v2, v4, vcc
	v_lshlrev_b32_e32 v86, 2, v4
	v_xor_b32_e32 v4, 8, v2
	v_cmp_lt_i32_e32 vcc, v4, v3
	s_mov_b32 s55, 0x17001000
	s_mov_b32 s54, 0x3fb504f3
	v_cndmask_b32_e32 v4, v2, v4, vcc
	v_lshlrev_b32_e32 v87, 2, v4
	v_xor_b32_e32 v4, 16, v2
	v_cmp_lt_i32_e32 vcc, v4, v3
	v_mov_b32_e32 v90, 0x3727c5ac
	s_mov_b32 s56, 0xf800000
	v_cndmask_b32_e32 v4, v2, v4, vcc
	v_lshlrev_b32_e32 v88, 2, v4
	v_xor_b32_e32 v4, 32, v2
	v_cmp_lt_i32_e32 vcc, v4, v3
	v_mov_b32_e32 v91, 0x260
	s_movk_i32 s57, 0x7fff
	v_cndmask_b32_e32 v2, v2, v4, vcc
	v_lshlrev_b32_e32 v89, 2, v2
	v_lshlrev_b64 v[2:3], 4, v[0:1]
	v_lshl_add_u64 v[4:5], s[26:27], 0, v[2:3]
	v_lshl_add_u64 v[2:3], s[28:29], 0, v[2:3]
	v_lshl_add_u64 v[8:9], v[4:5], 0, s[0:1]
	v_lshl_add_u64 v[10:11], v[2:3], 0, s[0:1]
	s_lshl_b64 s[0:1], s[30:31], 9
	s_add_u32 s44, s40, s0
	s_addc_u32 s45, s41, s1
	s_ashr_i32 s37, s36, 31
	s_lshl_b64 s[46:47], s[36:37], 9
	s_lshl_b64 s[0:1], s[30:31], 11
	s_add_u32 s48, s40, s0
	s_addc_u32 s49, s41, s1
	s_lshl_b64 s[52:53], s[36:37], 11
	s_movk_i32 s31, 0xf000
	s_mov_b32 s37, 0x17000000

.LBB0_917:
	s_or_b64 exec, exec, s[16:17]
.LBB0_918:
	s_or_b64 exec, exec, s[0:1]
	s_add_u32 s30, s40, 0x5000000
	s_waitcnt lgkmcnt(0)
	v_mov_b32_e32 v0, v180
	s_addc_u32 s31, s41, 0
	v_mov_b32_e32 v8, v182
	s_barrier
	s_cmpk_gt_i32 s2, 0xff
	v_readfirstlane_b32 s11, v8
	s_cbranch_scc1 .LBB0_942
	s_lshr_b32 s0, s3, 29
	s_add_i32 s12, s2, s0
	s_and_b32 s0, s12, -8
	s_sub_i32 s13, s2, s0
	s_cmp_gt_i32 s13, -1
	s_cbranch_scc0 .LBB0_921
	s_lshl_b32 s10, s13, 5
	s_cbranch_execz .LBB0_922
	s_branch .LBB0_923

.LBB0_1009:
	s_or_b64 exec, exec, s[16:17]
.LBB0_1010:
	s_or_b64 exec, exec, s[0:1]
	s_waitcnt lgkmcnt(0)
	v_mov_b32_e32 v0, v180
	v_mov_b32_e32 v8, v182
	s_barrier
	s_and_b64 vcc, exec, s[6:7]
	v_readfirstlane_b32 s10, v8
	s_cbranch_vccnz .LBB0_1038
	s_lshr_b32 s0, s3, 29
	s_add_i32 s11, s2, s0
	s_and_b32 s0, s11, -8
	s_sub_i32 s12, s2, s0
	s_cmp_gt_i32 s12, -1
	s_cbranch_scc0 .LBB0_1013
	s_lshl_b32 s16, s12, 6
	s_cbranch_execz .LBB0_1014
	s_branch .LBB0_1015

.LBB0_1089:
	s_or_b64 exec, exec, s[16:17]
.LBB0_1090:
	s_or_b64 exec, exec, s[0:1]
	s_waitcnt lgkmcnt(0)
	v_mov_b32_e32 v0, v180
	s_and_b64 vcc, exec, s[4:5]
	s_barrier
	s_cbranch_vccnz .LBB0_1093
	v_mbcnt_hi_u32_b32 v2, -1, v183
	v_and_b32_e32 v3, 64, v2
	v_add_u32_e32 v3, 64, v3
	v_xor_b32_e32 v4, 1, v2
	v_cmp_lt_i32_e32 vcc, v4, v3
	v_ashrrev_i32_e32 v1, 31, v0
	s_lshl_b32 s36, s33, 2
	v_cndmask_b32_e32 v4, v2, v4, vcc
	v_lshlrev_b32_e32 v84, 2, v4
	v_xor_b32_e32 v4, 2, v2
	v_cmp_lt_i32_e32 vcc, v4, v3
	s_mov_b64 s[0:1], 0x3000
	s_ashr_i32 s37, s36, 31
	v_cndmask_b32_e32 v4, v2, v4, vcc
	v_lshlrev_b32_e32 v85, 2, v4
	v_xor_b32_e32 v4, 4, v2
	v_cmp_lt_i32_e32 vcc, v4, v3
	s_lshl_b32 s44, s42, 5
	v_lshlrev_b64 v[12:13], 3, v[0:1]
	v_cndmask_b32_e32 v4, v2, v4, vcc
	v_lshlrev_b32_e32 v86, 2, v4
	v_xor_b32_e32 v4, 8, v2
	v_cmp_lt_i32_e32 vcc, v4, v3
	s_mov_b32 s57, 0x17001000
	s_mov_b32 s56, 0x3fb504f3
	v_cndmask_b32_e32 v4, v2, v4, vcc
	v_lshlrev_b32_e32 v87, 2, v4
	v_xor_b32_e32 v4, 16, v2
	v_cmp_lt_i32_e32 vcc, v4, v3
	v_mov_b32_e32 v90, 0x3727c5ac
	s_mov_b32 s58, 0xf800000
	v_cndmask_b32_e32 v4, v2, v4, vcc
	v_lshlrev_b32_e32 v88, 2, v4
	v_xor_b32_e32 v4, 32, v2
	v_cmp_lt_i32_e32 vcc, v4, v3
	v_mov_b32_e32 v91, 0x260
	s_movk_i32 s59, 0x7fff
	v_cndmask_b32_e32 v2, v2, v4, vcc
	v_lshlrev_b32_e32 v89, 2, v2
	v_lshlrev_b64 v[2:3], 4, v[0:1]
	v_lshl_add_u64 v[4:5], s[26:27], 0, v[2:3]
	v_lshl_add_u64 v[2:3], s[28:29], 0, v[2:3]
	v_lshl_add_u64 v[8:9], v[4:5], 0, s[0:1]
	v_lshl_add_u64 v[10:11], v[2:3], 0, s[0:1]
	s_lshl_b64 s[0:1], s[36:37], 9
	s_add_u32 s46, s40, s0
	s_addc_u32 s47, s41, s1
	s_ashr_i32 s45, s44, 31
	s_lshl_b64 s[48:49], s[44:45], 9
	s_lshl_b64 s[0:1], s[36:37], 11
	s_add_u32 s52, s40, s0
	s_addc_u32 s53, s41, s1
	s_lshl_b64 s[54:55], s[44:45], 11
	s_movk_i32 s37, 0xf000
	s_mov_b32 s45, 0x17000000

.LBB0_1144:
	s_or_b64 exec, exec, s[16:17]
.LBB0_1145:
	s_or_b64 exec, exec, s[0:1]
	s_waitcnt lgkmcnt(0)
	v_mov_b32_e32 v0, v180
	v_mov_b32_e32 v8, v182
	s_barrier
	s_and_b64 vcc, exec, s[6:7]
	v_readfirstlane_b32 s11, v8
	s_cbranch_vccnz .LBB0_1169
	s_lshr_b32 s0, s3, 29
	s_add_i32 s12, s2, s0
	s_and_b32 s0, s12, -8
	s_sub_i32 s13, s2, s0
	s_cmp_gt_i32 s13, -1
	s_cbranch_scc0 .LBB0_1148
	s_lshl_b32 s10, s13, 6
	s_cbranch_execz .LBB0_1149
	s_branch .LBB0_1150

.LBB0_1220:
	s_or_b64 exec, exec, s[16:17]
.LBB0_1221:
	s_or_b64 exec, exec, s[0:1]
	s_waitcnt lgkmcnt(0)
	v_mov_b32_e32 v0, v180
	v_mov_b32_e32 v6, v182
	s_barrier
	s_and_b64 vcc, exec, s[6:7]
	v_readfirstlane_b32 s18, v6
	s_cbranch_vccnz .LBB0_1242
	s_add_u32 s10, s40, 0x6000000
	s_addc_u32 s11, s41, 0
	s_lshl_b32 s0, s2, 8
	s_and_b32 s88, s0, 0xf00
	s_lshr_b32 s0, s2, 2
	s_ashr_i32 s16, s2, 6
	s_and_b32 s0, s0, 12
	s_ashr_i32 s17, s16, 31
	s_lshl_b32 s1, s0, 19
	s_lshl_b64 s[12:13], s[16:17], 18
	s_add_u32 s12, s12, s1
	s_addc_u32 s13, s13, 0
	s_lshl_b64 s[12:13], s[12:13], 1
	s_add_u32 s36, s30, s12
	s_addc_u32 s37, s31, s13
	s_add_u32 s44, s10, s12
	s_addc_u32 s45, s11, s13
	v_lshlrev_b32_e32 v0, 4, v6
	s_cmp_lg_u32 s88, 0
	v_mov_b32_e32 v1, 0
	s_cselect_b64 s[12:13], -1, 0
	s_cmp_eq_u32 s88, 0
	v_lshl_add_u64 v[4:5], s[36:37], 0, v[0:1]
	v_lshl_add_u64 v[2:3], s[44:45], 0, v[0:1]
	s_cbranch_scc1 .LBB0_1225
	s_lshl_b32 s1, s88, 7
	s_add_u32 s36, s1, 0xffffc000
	s_addc_u32 s37, 0, -1
	v_lshl_add_u64 v[8:9], v[4:5], 0, s[36:37]
	v_lshl_add_u64 v[10:11], v[2:3], 0, s[36:37]
	global_load_dwordx4 v[84:87], v[8:9], off nt
	global_load_dwordx4 v[80:83], v[10:11], off nt
	s_mov_b32 s1, 0
	s_andn2_b64 vcc, exec, s[12:13]
	s_mov_b32 s62, 1
	s_cbranch_vccnz .LBB0_1226

.LBB0_1293:
	s_or_b64 exec, exec, s[16:17]
.LBB0_1294:
	s_or_b64 exec, exec, s[0:1]
	s_waitcnt lgkmcnt(0)
	v_mov_b32_e32 v0, v180
	v_mov_b32_e32 v8, v182
	s_barrier
	s_and_b64 vcc, exec, s[6:7]
	v_readfirstlane_b32 s11, v8
	s_cbranch_vccnz .LBB0_1318
	s_lshr_b32 s0, s3, 29
	s_add_i32 s12, s2, s0
	s_and_b32 s0, s12, -8
	s_sub_i32 s13, s2, s0
	s_cmp_gt_i32 s13, -1
	s_cbranch_scc0 .LBB0_1297
	s_lshl_b32 s10, s13, 6
	s_cbranch_execz .LBB0_1298
	s_branch .LBB0_1299

.LBB0_1369:
	s_or_b64 exec, exec, s[16:17]
.LBB0_1370:
	s_or_b64 exec, exec, s[0:1]
	s_waitcnt lgkmcnt(0)
	v_mov_b32_e32 v0, v180
	s_and_b64 vcc, exec, s[4:5]
	s_barrier
	s_cbranch_vccnz .LBB0_1373
	v_mbcnt_hi_u32_b32 v2, -1, v183
	v_and_b32_e32 v3, 64, v2
	v_add_u32_e32 v3, 64, v3
	v_xor_b32_e32 v4, 1, v2
	v_cmp_lt_i32_e32 vcc, v4, v3
	v_ashrrev_i32_e32 v1, 31, v0
	s_lshl_b32 s30, s33, 2
	v_cndmask_b32_e32 v4, v2, v4, vcc
	v_lshlrev_b32_e32 v98, 2, v4
	v_xor_b32_e32 v4, 2, v2
	v_cmp_lt_i32_e32 vcc, v4, v3
	s_mov_b64 s[0:1], 0x4000
	s_ashr_i32 s31, s30, 31
	v_cndmask_b32_e32 v4, v2, v4, vcc
	v_lshlrev_b32_e32 v99, 2, v4
	v_xor_b32_e32 v4, 4, v2
	v_cmp_lt_i32_e32 vcc, v4, v3
	s_lshl_b32 s36, s42, 5
	v_lshlrev_b64 v[12:13], 3, v[0:1]
	v_cndmask_b32_e32 v4, v2, v4, vcc
	v_lshlrev_b32_e32 v100, 2, v4
	v_xor_b32_e32 v4, 8, v2
	v_cmp_lt_i32_e32 vcc, v4, v3
	s_mov_b32 s53, 0x17001000
	s_mov_b32 s52, 0x3fb504f3
	v_cndmask_b32_e32 v4, v2, v4, vcc
	v_lshlrev_b32_e32 v101, 2, v4
	v_xor_b32_e32 v4, 16, v2
	v_cmp_lt_i32_e32 vcc, v4, v3
	v_mov_b32_e32 v104, 0x3727c5ac
	s_mov_b32 s54, 0xf800000
	v_cndmask_b32_e32 v4, v2, v4, vcc
	v_lshlrev_b32_e32 v102, 2, v4
	v_xor_b32_e32 v4, 32, v2
	v_cmp_lt_i32_e32 vcc, v4, v3
	v_mov_b32_e32 v105, 0x260
	s_movk_i32 s55, 0x7fff
	v_cndmask_b32_e32 v2, v2, v4, vcc
	v_lshlrev_b32_e32 v103, 2, v2
	v_lshlrev_b64 v[2:3], 4, v[0:1]
	v_lshl_add_u64 v[4:5], s[26:27], 0, v[2:3]
	v_lshl_add_u64 v[2:3], s[28:29], 0, v[2:3]
	v_lshl_add_u64 v[8:9], v[4:5], 0, s[0:1]
	v_lshl_add_u64 v[10:11], v[2:3], 0, s[0:1]
	s_lshl_b64 s[0:1], s[30:31], 9
	s_add_u32 s44, s40, s0
	s_addc_u32 s45, s41, s1
	s_ashr_i32 s37, s36, 31
	s_lshl_b64 s[46:47], s[36:37], 9
	s_lshl_b64 s[0:1], s[30:31], 11
	s_add_u32 s48, s40, s0
	s_addc_u32 s49, s41, s1
	s_lshl_b64 s[50:51], s[36:37], 11
	s_movk_i32 s31, 0xf000
	s_mov_b32 s37, 0x17000000

.LBB0_1424:
	s_or_b64 exec, exec, s[16:17]
.LBB0_1425:
	s_or_b64 exec, exec, s[0:1]
	s_waitcnt lgkmcnt(0)
	v_mov_b32_e32 v0, v180
	v_mov_b32_e32 v9, v182
	s_barrier
	s_and_b64 vcc, exec, s[8:9]
	v_readfirstlane_b32 s9, v9
	s_cbranch_vccnz .LBB0_1441
	v_lshlrev_b32_e32 v0, 4, v9
	v_add_u32_e32 v1, 0x2000, v0
	v_ashrrev_i32_e32 v2, 31, v1
	v_lshrrev_b32_e32 v2, 22, v2
	v_add_u32_e32 v2, v1, v2
	v_ashrrev_i32_e32 v8, 10, v2
	v_mul_i32_i24_e32 v3, 0x400, v8
	v_sub_u32_e32 v1, v1, v3
	v_lshrrev_b32_e32 v3, 4, v1
	v_bitop3_b32 v1, v3, v1, 32 bitop3:0x6c
	v_ashrrev_i32_e32 v3, 31, v1
	v_lshrrev_b32_e32 v3, 26, v3
	s_add_u32 s52, s40, 0x2200000
	v_add_u32_e32 v3, v1, v3
	s_addc_u32 s53, s41, 0
	v_ashrrev_i32_e32 v10, 6, v3
	v_and_b32_e32 v3, 0xc0, v3
	s_lshr_b32 s0, s3, 29
	v_sub_u32_e32 v1, v1, v3
	v_mov_b32_e32 v3, 1
	s_add_i32 s0, s2, s0
	s_ashr_i32 s10, s9, 6
	v_lshlrev_b32_e32 v2, 5, v8
	v_ashrrev_i16_sdwa v1, v3, sext(v1) dst_sel:DWORD dst_unused:UNUSED_PAD src0_sel:DWORD src1_sel:BYTE_0
	s_ashr_i32 s1, s0, 3
	s_and_b32 s0, s0, -8
	s_ashr_i32 s12, s9, 8
	s_lshl_b32 s54, s10, 10
	v_and_b32_e32 v2, 32, v2
	v_bfe_i32 v11, v1, 0, 16
	s_sub_i32 s0, s2, s0
	v_add_u32_e32 v1, v2, v11
	v_lshlrev_b32_e32 v2, 3, v8
	s_cmp_lt_i32 s0, 0
	s_movk_i32 s55, 0x161
	v_and_b32_e32 v2, 0x1ffff0, v2
	s_cselect_b32 s8, s55, 0x160
	v_add_lshl_u32 v2, v10, v2, 11
	s_mul_i32 s0, s8, s0
	v_lshl_add_u32 v128, v1, 1, v2
	v_bfe_i32 v2, v9, 27, 1
	s_add_i32 s0, s0, s1
	v_lshrrev_b32_e32 v2, 22, v2
	s_mul_hi_i32 s1, s0, 0x2e8ba2e9
	v_add_u32_e32 v2, v0, v2
	s_lshr_b32 s8, s1, 31
	s_ashr_i32 s1, s1, 5
	v_and_b32_e32 v2, 0xfffffc00, v2
	s_add_i32 s1, s1, s8
	v_sub_u32_e32 v0, v0, v2
	s_lshl_b32 s11, s1, 3
	s_mulk_i32 s1, 0xb0
	v_lshrrev_b32_e32 v2, 4, v0
	s_sub_i32 s0, s0, s1
	v_bitop3_b32 v0, v2, v0, 32 bitop3:0x6c
	s_sext_i32_i16 s1, s0
	v_ashrrev_i32_e32 v2, 31, v0
	s_bfe_u32 s1, s1, 0x3001c
	v_ashrrev_i32_e32 v1, 31, v9
	v_lshrrev_b32_e32 v2, 26, v2
	s_add_i32 s1, s0, s1
	v_lshrrev_b32_e32 v1, 26, v1
	v_add_u32_e32 v2, v0, v2
	s_sext_i32_i16 s8, s1
	s_and_b32 s1, s1, 0xfff8
	v_add_u32_e32 v1, v9, v1
	v_ashrrev_i32_e32 v13, 6, v2
	v_and_b32_e32 v2, 0xc0, v2
	s_sub_i32 s0, s0, s1
	v_ashrrev_i32_e32 v12, 6, v1
	v_sub_u32_e32 v0, v0, v2
	s_sext_i32_i16 s0, s0
	v_lshlrev_b32_e32 v1, 5, v12
	v_ashrrev_i16_sdwa v0, v3, sext(v0) dst_sel:DWORD dst_unused:UNUSED_PAD src0_sel:DWORD src1_sel:BYTE_0
	s_lshr_b32 s8, s8, 3
	s_add_i32 s44, s11, s0
	v_and_b32_e32 v1, 32, v1
	v_bfe_i32 v14, v0, 0, 16
	s_ashr_i32 s45, s44, 31
	s_bfe_i64 s[16:17], s[8:9], 0x100000
	v_add_u32_e32 v0, v1, v14
	v_lshlrev_b32_e32 v1, 3, v12
	s_lshl_b64 s[0:1], s[44:45], 19
	s_lshl_b64 s[16:17], s[16:17], 19
	v_and_b32_e32 v1, 0x1ffff0, v1
	s_add_u32 s48, s52, s16
	v_add_lshl_u32 v1, v13, v1, 11
	s_addc_u32 s49, s53, s17
	s_add_i32 s45, s54, 0
	v_lshl_add_u32 v130, v0, 1, v1
	s_add_i32 m0, s45, 0x10000
	v_mov_b32_e32 v131, 0
	global_load_lds_dwordx4 v130, s[48:49]
	s_add_i32 m0, s45, 0x12000
	s_add_u32 s16, s48, 0x40000
	global_load_lds_dwordx4 v128, s[48:49]
	s_addc_u32 s17, s49, 0
	s_add_i32 m0, s45, 0x14000
	v_mov_b32_e32 v129, v131
	global_load_lds_dwordx4 v130, s[16:17]
	s_add_i32 m0, s45, 0x16000
	s_add_u32 s46, s80, s0
	s_addc_u32 s47, s81, s1
	s_add_i32 s56, s45, 0x2000
	global_load_lds_dwordx4 v128, s[16:17]
	s_mov_b32 m0, s45
	s_add_u32 s0, s46, 0x40000
	global_load_lds_dwordx4 v130, s[46:47]
	s_mov_b32 m0, s56
	s_addc_u32 s1, s47, 0
	s_add_i32 s57, s45, 0x4000
	global_load_lds_dwordx4 v128, s[46:47]
	s_mov_b32 m0, s57
	s_add_i32 s58, s45, 0x6000
	global_load_lds_dwordx4 v130, s[0:1]
	s_mov_b32 m0, s58
	s_cmp_eq_u32 s12, 1
	global_load_lds_dwordx4 v128, s[0:1]
	s_mov_b32 s59, 0
	v_lshl_add_u64 v[6:7], s[48:49], 0, v[130:131]
	v_lshl_add_u64 v[4:5], s[48:49], 0, v[128:129]
	v_lshl_add_u64 v[0:1], s[46:47], 0, v[130:131]
	s_cselect_b64 s[0:1], -1, 0
	s_cmp_lg_u32 s12, 1
	v_lshl_add_u64 v[2:3], s[46:47], 0, v[128:129]
	s_cbranch_scc1 .LBB0_1428
	s_barrier

.LBB0_1492:
	s_or_b64 exec, exec, s[12:13]
.LBB0_1493:
	s_or_b64 exec, exec, s[0:1]
	s_waitcnt lgkmcnt(0)
	v_mov_b32_e32 v0, v180
	s_barrier
	s_and_b64 vcc, exec, s[6:7]
	v_readfirstlane_b32 s6, v182
	s_cbranch_vccnz .LBB0_1521
	s_lshr_b32 s0, s3, 29
	s_add_i32 s8, s2, s0
	s_and_b32 s0, s8, -8
	s_sub_i32 s7, s2, s0
	s_cmp_gt_i32 s7, -1
	s_cbranch_scc0 .LBB0_1496
	s_lshl_b32 s10, s7, 6
	s_ashr_i32 s0, s8, 3
	s_cbranch_execz .LBB0_1497
	s_branch .LBB0_1498

.LBB0_1572:
	s_or_b64 exec, exec, s[8:9]
.LBB0_1573:
	s_or_b64 exec, exec, s[0:1]
	s_and_b64 vcc, exec, s[4:5]
	s_waitcnt lgkmcnt(0)
	s_barrier
	s_cbranch_vccnz .LBB0_1576
	v_mbcnt_hi_u32_b32 v0, -1, v183
	v_and_b32_e32 v1, 64, v0
	v_add_u32_e32 v1, 64, v1
	v_xor_b32_e32 v2, 1, v0
	v_cmp_lt_i32_e32 vcc, v2, v1
	v_ashrrev_i32_e32 v181, 31, v180
	s_lshl_b32 s10, s33, 2
	v_cndmask_b32_e32 v2, v0, v2, vcc
	v_lshlrev_b32_e32 v84, 2, v2
	v_xor_b32_e32 v2, 2, v0
	v_cmp_lt_i32_e32 vcc, v2, v1
	s_mov_b64 s[0:1], 0x5000
	s_ashr_i32 s11, s10, 31
	v_cndmask_b32_e32 v2, v0, v2, vcc
	v_lshlrev_b32_e32 v85, 2, v2
	v_xor_b32_e32 v2, 4, v0
	v_cmp_lt_i32_e32 vcc, v2, v1
	s_lshl_b32 s12, s42, 5
	v_lshlrev_b64 v[12:13], 3, v[180:181]
	v_cndmask_b32_e32 v2, v0, v2, vcc
	v_lshlrev_b32_e32 v86, 2, v2
	v_xor_b32_e32 v2, 8, v0
	v_cmp_lt_i32_e32 vcc, v2, v1
	s_mov_b32 s25, 0x17001000
	s_mov_b32 s24, 0x3fb504f3
	v_cndmask_b32_e32 v2, v0, v2, vcc
	v_lshlrev_b32_e32 v87, 2, v2
	v_xor_b32_e32 v2, 16, v0
	v_cmp_lt_i32_e32 vcc, v2, v1
	v_mov_b32_e32 v90, 0x3727c5ac
	v_mov_b32_e32 v91, 0x260
	v_cndmask_b32_e32 v2, v0, v2, vcc
	v_lshlrev_b32_e32 v88, 2, v2
	v_xor_b32_e32 v2, 32, v0
	v_cmp_lt_i32_e32 vcc, v2, v1
	s_nop 1
	v_cndmask_b32_e32 v0, v0, v2, vcc
	v_lshlrev_b32_e32 v89, 2, v0
	v_lshlrev_b64 v[0:1], 4, v[180:181]
	v_lshl_add_u64 v[2:3], s[26:27], 0, v[0:1]
	v_lshl_add_u64 v[8:9], v[2:3], 0, s[0:1]
	v_lshl_add_u64 v[2:3], s[28:29], 0, v[0:1]
	v_lshl_add_u64 v[10:11], v[2:3], 0, s[0:1]
	s_lshl_b64 s[0:1], s[10:11], 9
	s_add_u32 s14, s40, s0
	s_addc_u32 s15, s41, s1
	s_ashr_i32 s13, s12, 31
	s_lshl_b64 s[16:17], s[12:13], 9
	s_lshl_b64 s[0:1], s[10:11], 11
	s_add_u32 s18, s40, s0
	s_addc_u32 s19, s41, s1
	s_lshl_b64 s[20:21], s[12:13], 11
	s_lshl_b64 s[0:1], s[10:11], 12
	s_add_u32 s0, s38, s0
	s_addc_u32 s1, s39, s1
	v_lshl_add_u64 v[14:15], s[0:1], 0, v[0:1]
	s_lshl_b64 s[22:23], s[12:13], 12
	s_movk_i32 s11, 0xf000
	s_mov_b32 s13, 0x17000000
	s_mov_b32 s26, 0xf800000
	s_movk_i32 s27, 0x1000
	s_movk_i32 s28, 0x2000
	s_movk_i32 s29, 0x3000
